# v16: residual/merge epilogues (P4, P5, P8) all with gate/base loads 4 row-steps ahead; plus GLA prefix unroll, SGPR-base LDS-DMA, P6 param reuse/prefetch, P0 adaLN, b64 zeroing
# speedup vs baseline: 1.0008x; 1.0008x over previous
; __device__ __forceinline__ float bf_lo(unsigned u) { return __uint_as_float(u << 16); }
; __device__ __forceinline__ float bf_hi(unsigned u) { return __uint_as_float(u & 0xffff0000u); }
;     __device__ __forceinline__ void mid(AccT& acc, const Unit& u, int wr, int wc, int fr, int fq) const {
;         const size_t off0 = (size_t)(u.pm * BM + wr * 64 + fr) * 1024 + u.pn * BM + wc * 32 + 8 * fq;
; #pragma unroll
;         for (int ai = 0; ai < 2; ++ai)
; #pragma unroll
;             for (int m = 0; m < 4; ++m)
; #pragma unroll
;                 for (int bj = 0; bj < 2; ++bj) { const size_t off = off0 + (size_t)(ai * HALF + m * 16) * 1024 + bj * HALF;
;                     const u32x4 a = *(const u32x4*)(G1 + off);
;                     const f32x4 r0 = (f32x4){bf_lo(a.x), bf_hi(a.x), bf_lo(a.y), bf_hi(a.y)}, r1 = (f32x4){bf_lo(a.z), bf_hi(a.z), bf_lo(a.w), bf_hi(a.w)};
;                     acc[ai][bj][m][0] = acc[ai][bj][m][0] * r0; acc[ai][bj][m][1] = acc[ai][bj][m][1] * r1; }
.LBB0_473:
	s_lshl_b32 s30, s70, 8
	v_lshlrev_b64 v[128:129], 11, v[132:133]
	s_ashr_i32 s31, s30, 31
	v_lshl_add_u64 v[128:129], s[10:11], 0, v[128:129]
	v_lshl_add_u64 v[128:129], s[30:31], 1, v[128:129]
	v_lshl_add_u64 v[128:129], v[128:129], 0, s[6:7]
	v_lshl_add_u64 v[184:185], v[128:129], 0, v[172:173]
	v_subrev_u32_e32 v222, s10, v184
	global_load_dwordx4 v[128:131], v222, s[10:11]
	global_load_dwordx4 v[132:135], v222, s[10:11] offset:256
	v_add_u32_e32 v222, 0x8000, v222
	global_load_dwordx4 v[136:139], v222, s[10:11]
	global_load_dwordx4 v[140:143], v222, s[10:11] offset:256
	s_waitcnt vmcnt(3)
	v_lshlrev_b32_e32 v218, 16, v128
	v_and_b32_e32 v219, 0xffff0000, v128
	v_pk_mul_f32 v[124:125], v[124:125], v[218:219]
	v_lshlrev_b32_e32 v218, 16, v129
	v_and_b32_e32 v219, 0xffff0000, v129
	v_pk_mul_f32 v[126:127], v[126:127], v[218:219]
	v_lshlrev_b32_e32 v220, 16, v130
	v_and_b32_e32 v221, 0xffff0000, v130
	v_pk_mul_f32 v[120:121], v[120:121], v[220:221]
	v_lshlrev_b32_e32 v220, 16, v131
	v_and_b32_e32 v221, 0xffff0000, v131
	v_add_u32_e32 v222, 0x8000, v222
	global_load_dwordx4 v[128:131], v222, s[10:11]
	v_pk_mul_f32 v[122:123], v[122:123], v[220:221]
	s_waitcnt vmcnt(3)
	v_lshlrev_b32_e32 v218, 16, v132
	v_and_b32_e32 v219, 0xffff0000, v132
	v_pk_mul_f32 v[92:93], v[92:93], v[218:219]
	v_lshlrev_b32_e32 v218, 16, v133
	v_and_b32_e32 v219, 0xffff0000, v133
	v_pk_mul_f32 v[94:95], v[94:95], v[218:219]
	v_lshlrev_b32_e32 v220, 16, v134
	v_and_b32_e32 v221, 0xffff0000, v134
	v_pk_mul_f32 v[88:89], v[88:89], v[220:221]
	v_lshlrev_b32_e32 v220, 16, v135
	v_and_b32_e32 v221, 0xffff0000, v135
	global_load_dwordx4 v[132:135], v222, s[10:11] offset:256
	v_pk_mul_f32 v[90:91], v[90:91], v[220:221]
	s_waitcnt vmcnt(3)
	v_lshlrev_b32_e32 v218, 16, v136
	v_and_b32_e32 v219, 0xffff0000, v136
	v_pk_mul_f32 v[116:117], v[116:117], v[218:219]
	v_lshlrev_b32_e32 v218, 16, v137
	v_and_b32_e32 v219, 0xffff0000, v137
	v_pk_mul_f32 v[118:119], v[118:119], v[218:219]
	v_lshlrev_b32_e32 v220, 16, v138
	v_and_b32_e32 v221, 0xffff0000, v138
	v_pk_mul_f32 v[112:113], v[112:113], v[220:221]
	v_lshlrev_b32_e32 v220, 16, v139
	v_and_b32_e32 v221, 0xffff0000, v139
	v_add_u32_e32 v222, 0x8000, v222
	global_load_dwordx4 v[136:139], v222, s[10:11]
	v_pk_mul_f32 v[114:115], v[114:115], v[220:221]
	s_waitcnt vmcnt(3)
	v_lshlrev_b32_e32 v218, 16, v140
	v_and_b32_e32 v219, 0xffff0000, v140
	v_pk_mul_f32 v[84:85], v[84:85], v[218:219]
	v_lshlrev_b32_e32 v218, 16, v141
	v_and_b32_e32 v219, 0xffff0000, v141
	v_pk_mul_f32 v[86:87], v[86:87], v[218:219]
	v_lshlrev_b32_e32 v220, 16, v142
	v_and_b32_e32 v221, 0xffff0000, v142
	v_pk_mul_f32 v[80:81], v[80:81], v[220:221]
	v_lshlrev_b32_e32 v220, 16, v143
	v_and_b32_e32 v221, 0xffff0000, v143
	global_load_dwordx4 v[140:143], v222, s[10:11] offset:256
	v_pk_mul_f32 v[82:83], v[82:83], v[220:221]
	s_waitcnt vmcnt(3)
	v_lshlrev_b32_e32 v218, 16, v128
	v_and_b32_e32 v219, 0xffff0000, v128
	v_pk_mul_f32 v[108:109], v[108:109], v[218:219]
	v_lshlrev_b32_e32 v218, 16, v129
	v_and_b32_e32 v219, 0xffff0000, v129
	v_pk_mul_f32 v[110:111], v[110:111], v[218:219]
	v_lshlrev_b32_e32 v220, 16, v130
	v_and_b32_e32 v221, 0xffff0000, v130
	v_pk_mul_f32 v[104:105], v[104:105], v[220:221]
	v_lshlrev_b32_e32 v220, 16, v131
	v_and_b32_e32 v221, 0xffff0000, v131
	v_add_u32_e32 v222, 0x28000, v222
	global_load_dwordx4 v[128:131], v222, s[10:11]
	v_pk_mul_f32 v[106:107], v[106:107], v[220:221]
	s_waitcnt vmcnt(3)
	v_lshlrev_b32_e32 v218, 16, v132
	v_and_b32_e32 v219, 0xffff0000, v132
	v_pk_mul_f32 v[76:77], v[76:77], v[218:219]
	v_lshlrev_b32_e32 v218, 16, v133
	v_and_b32_e32 v219, 0xffff0000, v133
	v_pk_mul_f32 v[78:79], v[78:79], v[218:219]
	v_lshlrev_b32_e32 v220, 16, v134
	v_and_b32_e32 v221, 0xffff0000, v134
	v_pk_mul_f32 v[72:73], v[72:73], v[220:221]
	v_lshlrev_b32_e32 v220, 16, v135
	v_and_b32_e32 v221, 0xffff0000, v135
	global_load_dwordx4 v[132:135], v222, s[10:11] offset:256
	v_pk_mul_f32 v[74:75], v[74:75], v[220:221]
	s_waitcnt vmcnt(3)
	v_lshlrev_b32_e32 v218, 16, v136
	v_and_b32_e32 v219, 0xffff0000, v136
	v_pk_mul_f32 v[100:101], v[100:101], v[218:219]
	v_lshlrev_b32_e32 v218, 16, v137
	v_and_b32_e32 v219, 0xffff0000, v137
	v_pk_mul_f32 v[102:103], v[102:103], v[218:219]
	v_lshlrev_b32_e32 v220, 16, v138
	v_and_b32_e32 v221, 0xffff0000, v138
	v_pk_mul_f32 v[96:97], v[96:97], v[220:221]
	v_lshlrev_b32_e32 v220, 16, v139
	v_and_b32_e32 v221, 0xffff0000, v139
	v_add_u32_e32 v222, 0x8000, v222
	global_load_dwordx4 v[136:139], v222, s[10:11]
	v_pk_mul_f32 v[98:99], v[98:99], v[220:221]
	s_waitcnt vmcnt(3)
; __device__ __forceinline__ float bf_lo(unsigned u) { return __uint_as_float(u << 16); }
; __device__ __forceinline__ float bf_hi(unsigned u) { return __uint_as_float(u & 0xffff0000u); }
;     __device__ __forceinline__ void mid(AccT& acc, const Unit& u, int wr, int wc, int fr, int fq) const {
;         const size_t off0 = (size_t)(u.pm * BM + wr * 64 + fr) * 1024 + u.pn * BM + wc * 32 + 8 * fq;
; #pragma unroll
;         for (int ai = 0; ai < 2; ++ai)
; #pragma unroll
;             for (int m = 0; m < 4; ++m)
; #pragma unroll
;                 for (int bj = 0; bj < 2; ++bj) { const size_t off = off0 + (size_t)(ai * HALF + m * 16) * 1024 + bj * HALF;
;                     const u32x4 a = *(const u32x4*)(G1 + off);
;                     const f32x4 r0 = (f32x4){bf_lo(a.x), bf_hi(a.x), bf_lo(a.y), bf_hi(a.y)}, r1 = (f32x4){bf_lo(a.z), bf_hi(a.z), bf_lo(a.w), bf_hi(a.w)};
;                     acc[ai][bj][m][0] = acc[ai][bj][m][0] * r0; acc[ai][bj][m][1] = acc[ai][bj][m][1] * r1; }
;     }
	v_lshlrev_b32_e32 v218, 16, v140
	v_and_b32_e32 v219, 0xffff0000, v140
	v_pk_mul_f32 v[68:69], v[68:69], v[218:219]
	v_lshlrev_b32_e32 v218, 16, v141
	v_and_b32_e32 v219, 0xffff0000, v141
	v_pk_mul_f32 v[70:71], v[70:71], v[218:219]
	v_lshlrev_b32_e32 v220, 16, v142
	v_and_b32_e32 v221, 0xffff0000, v142
	v_pk_mul_f32 v[64:65], v[64:65], v[220:221]
	v_lshlrev_b32_e32 v220, 16, v143
	v_and_b32_e32 v221, 0xffff0000, v143
	global_load_dwordx4 v[140:143], v222, s[10:11] offset:256
	v_pk_mul_f32 v[66:67], v[66:67], v[220:221]
	s_waitcnt vmcnt(3)
	v_lshlrev_b32_e32 v218, 16, v128
	v_and_b32_e32 v219, 0xffff0000, v128
	v_pk_mul_f32 v[60:61], v[60:61], v[218:219]
	v_lshlrev_b32_e32 v218, 16, v129
	v_and_b32_e32 v219, 0xffff0000, v129
	v_pk_mul_f32 v[62:63], v[62:63], v[218:219]
	v_lshlrev_b32_e32 v220, 16, v130
	v_and_b32_e32 v221, 0xffff0000, v130
	v_pk_mul_f32 v[56:57], v[56:57], v[220:221]
	v_lshlrev_b32_e32 v220, 16, v131
	v_and_b32_e32 v221, 0xffff0000, v131
	v_add_u32_e32 v222, 0x8000, v222
	global_load_dwordx4 v[128:131], v222, s[10:11]
	v_pk_mul_f32 v[58:59], v[58:59], v[220:221]
	s_waitcnt vmcnt(3)
	v_lshlrev_b32_e32 v218, 16, v132
	v_and_b32_e32 v219, 0xffff0000, v132
	v_pk_mul_f32 v[28:29], v[28:29], v[218:219]
	v_lshlrev_b32_e32 v218, 16, v133
	v_and_b32_e32 v219, 0xffff0000, v133
	v_pk_mul_f32 v[30:31], v[30:31], v[218:219]
	v_lshlrev_b32_e32 v220, 16, v134
	v_and_b32_e32 v221, 0xffff0000, v134
	v_pk_mul_f32 v[24:25], v[24:25], v[220:221]
	v_lshlrev_b32_e32 v220, 16, v135
	v_and_b32_e32 v221, 0xffff0000, v135
	global_load_dwordx4 v[132:135], v222, s[10:11] offset:256
	v_pk_mul_f32 v[26:27], v[26:27], v[220:221]
	s_waitcnt vmcnt(3)
	v_lshlrev_b32_e32 v218, 16, v136
	v_and_b32_e32 v219, 0xffff0000, v136
	v_pk_mul_f32 v[52:53], v[52:53], v[218:219]
	v_lshlrev_b32_e32 v218, 16, v137
	v_and_b32_e32 v219, 0xffff0000, v137
	v_pk_mul_f32 v[54:55], v[54:55], v[218:219]
	v_lshlrev_b32_e32 v220, 16, v138
	v_and_b32_e32 v221, 0xffff0000, v138
	v_pk_mul_f32 v[48:49], v[48:49], v[220:221]
	v_lshlrev_b32_e32 v220, 16, v139
	v_and_b32_e32 v221, 0xffff0000, v139
	v_add_u32_e32 v222, 0x8000, v222
	global_load_dwordx4 v[136:139], v222, s[10:11]
	v_pk_mul_f32 v[50:51], v[50:51], v[220:221]
	s_waitcnt vmcnt(3)
	v_lshlrev_b32_e32 v218, 16, v140
	v_and_b32_e32 v219, 0xffff0000, v140
	v_pk_mul_f32 v[20:21], v[20:21], v[218:219]
	v_lshlrev_b32_e32 v218, 16, v141
	v_and_b32_e32 v219, 0xffff0000, v141
	v_pk_mul_f32 v[22:23], v[22:23], v[218:219]
	v_lshlrev_b32_e32 v220, 16, v142
	v_and_b32_e32 v221, 0xffff0000, v142
	v_pk_mul_f32 v[16:17], v[16:17], v[220:221]
	v_lshlrev_b32_e32 v220, 16, v143
	v_and_b32_e32 v221, 0xffff0000, v143
	global_load_dwordx4 v[140:143], v222, s[10:11] offset:256
	v_pk_mul_f32 v[18:19], v[18:19], v[220:221]
	s_waitcnt vmcnt(3)
	v_lshlrev_b32_e32 v218, 16, v128
	v_and_b32_e32 v219, 0xffff0000, v128
	v_pk_mul_f32 v[44:45], v[44:45], v[218:219]
	v_lshlrev_b32_e32 v218, 16, v129
	v_and_b32_e32 v219, 0xffff0000, v129
	v_pk_mul_f32 v[46:47], v[46:47], v[218:219]
	v_lshlrev_b32_e32 v220, 16, v130
	v_and_b32_e32 v221, 0xffff0000, v130
	v_pk_mul_f32 v[40:41], v[40:41], v[220:221]
	v_lshlrev_b32_e32 v220, 16, v131
	v_and_b32_e32 v221, 0xffff0000, v131
	v_pk_mul_f32 v[42:43], v[42:43], v[220:221]
	s_waitcnt vmcnt(2)
	v_lshlrev_b32_e32 v218, 16, v132
	v_and_b32_e32 v219, 0xffff0000, v132
	v_pk_mul_f32 v[12:13], v[12:13], v[218:219]
	v_lshlrev_b32_e32 v218, 16, v133
	v_and_b32_e32 v219, 0xffff0000, v133
	v_pk_mul_f32 v[14:15], v[14:15], v[218:219]
	v_lshlrev_b32_e32 v220, 16, v134
	v_and_b32_e32 v221, 0xffff0000, v134
	v_pk_mul_f32 v[8:9], v[8:9], v[220:221]
	v_lshlrev_b32_e32 v220, 16, v135
	v_and_b32_e32 v221, 0xffff0000, v135
	v_pk_mul_f32 v[10:11], v[10:11], v[220:221]
	s_waitcnt vmcnt(1)
	v_lshlrev_b32_e32 v218, 16, v136
	v_and_b32_e32 v219, 0xffff0000, v136
	v_pk_mul_f32 v[36:37], v[36:37], v[218:219]
	v_lshlrev_b32_e32 v218, 16, v137
	v_and_b32_e32 v219, 0xffff0000, v137
	v_pk_mul_f32 v[38:39], v[38:39], v[218:219]
	v_lshlrev_b32_e32 v220, 16, v138
	v_and_b32_e32 v221, 0xffff0000, v138
	v_pk_mul_f32 v[32:33], v[32:33], v[220:221]
	v_lshlrev_b32_e32 v220, 16, v139
	v_and_b32_e32 v221, 0xffff0000, v139
	v_pk_mul_f32 v[34:35], v[34:35], v[220:221]
	s_waitcnt vmcnt(0)
	v_lshlrev_b32_e32 v218, 16, v140
	v_and_b32_e32 v219, 0xffff0000, v140
	v_pk_mul_f32 v[4:5], v[4:5], v[218:219]
	v_lshlrev_b32_e32 v218, 16, v141
	v_and_b32_e32 v219, 0xffff0000, v141
	v_pk_mul_f32 v[6:7], v[6:7], v[218:219]
	v_lshlrev_b32_e32 v220, 16, v142
	v_and_b32_e32 v221, 0xffff0000, v142
	v_pk_mul_f32 v[0:1], v[0:1], v[220:221]
	v_lshlrev_b32_e32 v220, 16, v143
	v_and_b32_e32 v221, 0xffff0000, v143
	v_pk_mul_f32 v[2:3], v[2:3], v[220:221]

; __device__ __forceinline__ unsigned pk2(float lo, float hi) { f32x2 v = {lo, hi}; bf16x2_t b = __builtin_convertvector(v, bf16x2_t); return __builtin_bit_cast(unsigned, b); }
; __device__ __forceinline__ float bf_lo(unsigned u) { return __uint_as_float(u << 16); }
; __device__ __forceinline__ float bf_hi(unsigned u) { return __uint_as_float(u & 0xffff0000u); }
;     __device__ __forceinline__ void operator()(const AccT& acc, const Unit& u, int wr, int wc, int fr, int fq) const {
;         const int row0 = u.pm * BM + wr * 64 + fr; const int col0 = u.pn * BM + wc * 32 + 8 * fq; const int b = row0 >> 12;
;         f32x4 gt[2][2];
; #pragma unroll
;         for (int bj = 0; bj < 2; ++bj)
; #pragma unroll
;             for (int n = 0; n < 2; ++n) gt[bj][n] = *(const f32x4*)(gate + (size_t)b * NMOD + col0 + bj * HALF + n * 4);
; #pragma unroll
;         for (int ai = 0; ai < 2; ++ai)
; #pragma unroll
;             for (int m = 0; m < 4; ++m) { const size_t off = (size_t)(row0 + ai * HALF + m * 16) * DM + col0;
; #pragma unroll
;                 for (int bj = 0; bj < 2; ++bj) { f32x4 b0, b1;
;                     if constexpr (BB) { const u32x4 w = *(const u32x4*)((const bf16_t*)base + off + bj * HALF);
;                         b0 = (f32x4){bf_lo(w.x), bf_hi(w.x), bf_lo(w.y), bf_hi(w.y)}; b1 = (f32x4){bf_lo(w.z), bf_hi(w.z), bf_lo(w.w), bf_hi(w.w)}; }
;                     else { b0 = __builtin_nontemporal_load((const f32x4*)((const float*)base + off + bj * HALF)); b1 = __builtin_nontemporal_load((const f32x4*)((const float*)base + off + bj * HALF + 4)); }
;                     const f32x4 o0 = b0 + gt[bj][0] * acc[ai][bj][m][0], o1 = b1 + gt[bj][1] * acc[ai][bj][m][1];
;                     if constexpr (OB) { u32x4 w; w.x = pk2(o0[0], o0[1]); w.y = pk2(o0[2], o0[3]); w.z = pk2(o1[0], o1[1]); w.w = pk2(o1[2], o1[3]);
;                         *(u32x4*)((bf16_t*)out + off + bj * HALF) = w; }
;                     else { __builtin_nontemporal_store(o0, (f32x4*)((float*)out + off + bj * HALF)); __builtin_nontemporal_store(o1, (f32x4*)((float*)out + off + bj * HALF + 4)); } } }
;     }
.LBB0_556:
	v_readlane_b32 s36, v236, 10
	v_readlane_b32 s37, v236, 11
	s_lshl_b32 s23, s30, 8
	s_add_i32 s23, s23, s53
	v_or_b32_e32 v163, s23, v164
	v_lshl_or_b32 v162, s50, 8, v166
	s_ashr_i32 s25, s23, 12
	v_lshl_add_u32 v160, v163, 10, v162
	s_mul_hi_i32 s35, s25, 0x6000
	s_mulk_i32 s25, 0x6000
	v_lshlrev_b32_e32 v162, 2, v162
	s_add_u32 s34, s75, s25
	s_addc_u32 s35, s52, s35
	v_lshlrev_b32_e32 v161, 1, v160
	v_lshlrev_b32_e32 v160, 2, v160
	global_load_dwordx4 v[140:143], v162, s[34:35]
	global_load_dwordx4 v[136:139], v162, s[34:35] offset:16
	global_load_dwordx4 v[132:135], v162, s[34:35] offset:512
	global_load_dwordx4 v[128:131], v162, s[34:35] offset:528
	global_load_dwordx4 v[170:173], v160, s[36:37] nt
	global_load_dwordx4 v[176:179], v160, s[36:37] offset:16 nt
	global_load_dwordx4 v[180:183], v160, s[36:37] offset:512 nt
	global_load_dwordx4 v[184:187], v160, s[36:37] offset:528 nt
	v_add_u32_e32 v160, 0x10000, v160
	global_load_dwordx4 v[188:191], v160, s[36:37] nt
	global_load_dwordx4 v[192:195], v160, s[36:37] offset:16 nt
	global_load_dwordx4 v[196:199], v160, s[36:37] offset:512 nt
	global_load_dwordx4 v[200:203], v160, s[36:37] offset:528 nt
	s_waitcnt vmcnt(6)
	v_pk_fma_f32 v[126:127], v[126:127], v[142:143], v[172:173]
	v_pk_fma_f32 v[124:125], v[124:125], v[140:141], v[170:171]
	v_pk_fma_f32 v[122:123], v[122:123], v[138:139], v[178:179]
	v_pk_fma_f32 v[120:121], v[120:121], v[136:137], v[176:177]
	v_add_u32_e32 v160, 0x10000, v160
	global_load_dwordx4 v[170:173], v160, s[36:37] nt
	global_load_dwordx4 v[176:179], v160, s[36:37] offset:16 nt
	v_cvt_pk_bf16_f32 v124, v124, v125
	v_cvt_pk_bf16_f32 v125, v126, v127
	v_cvt_pk_bf16_f32 v126, v120, v121
	v_cvt_pk_bf16_f32 v127, v122, v123
	global_store_dwordx4 v161, v[124:127], s[8:9]
	s_waitcnt vmcnt(7)
	v_pk_fma_f32 v[118:119], v[118:119], v[134:135], v[182:183]
	v_pk_fma_f32 v[116:117], v[116:117], v[132:133], v[180:181]
	v_pk_fma_f32 v[114:115], v[114:115], v[130:131], v[186:187]
	v_pk_fma_f32 v[112:113], v[112:113], v[128:129], v[184:185]
	global_load_dwordx4 v[180:183], v160, s[36:37] offset:512 nt
	global_load_dwordx4 v[184:187], v160, s[36:37] offset:528 nt
	v_cvt_pk_bf16_f32 v116, v116, v117
	v_cvt_pk_bf16_f32 v117, v118, v119
	v_cvt_pk_bf16_f32 v118, v112, v113
	v_cvt_pk_bf16_f32 v119, v114, v115
	global_store_dwordx4 v161, v[116:119], s[8:9] offset:256
	v_add_u32_e32 v161, 0x8000, v161
	s_waitcnt vmcnt(8)
	v_pk_fma_f32 v[110:111], v[110:111], v[142:143], v[190:191]
	v_pk_fma_f32 v[108:109], v[108:109], v[140:141], v[188:189]
	v_pk_fma_f32 v[106:107], v[106:107], v[138:139], v[194:195]
	v_pk_fma_f32 v[104:105], v[104:105], v[136:137], v[192:193]
	v_add_u32_e32 v160, 0x10000, v160
	global_load_dwordx4 v[188:191], v160, s[36:37] nt
	global_load_dwordx4 v[192:195], v160, s[36:37] offset:16 nt
	v_cvt_pk_bf16_f32 v108, v108, v109
	v_cvt_pk_bf16_f32 v109, v110, v111
	v_cvt_pk_bf16_f32 v110, v104, v105
	v_cvt_pk_bf16_f32 v111, v106, v107
	global_store_dwordx4 v161, v[108:111], s[8:9]
	s_waitcnt vmcnt(9)
	v_pk_fma_f32 v[102:103], v[102:103], v[134:135], v[198:199]
	v_pk_fma_f32 v[100:101], v[100:101], v[132:133], v[196:197]
	v_pk_fma_f32 v[98:99], v[98:99], v[130:131], v[202:203]
	v_pk_fma_f32 v[96:97], v[96:97], v[128:129], v[200:201]
	global_load_dwordx4 v[196:199], v160, s[36:37] offset:512 nt
	global_load_dwordx4 v[200:203], v160, s[36:37] offset:528 nt
	v_cvt_pk_bf16_f32 v100, v100, v101
	v_cvt_pk_bf16_f32 v101, v102, v103
	v_cvt_pk_bf16_f32 v102, v96, v97
	v_cvt_pk_bf16_f32 v103, v98, v99
	global_store_dwordx4 v161, v[100:103], s[8:9] offset:256
	v_add_u32_e32 v161, 0x8000, v161
	s_waitcnt vmcnt(10)
	v_pk_fma_f32 v[94:95], v[94:95], v[142:143], v[172:173]
	v_pk_fma_f32 v[92:93], v[92:93], v[140:141], v[170:171]
	v_pk_fma_f32 v[90:91], v[90:91], v[138:139], v[178:179]
	v_pk_fma_f32 v[88:89], v[88:89], v[136:137], v[176:177]
	v_add_u32_e32 v160, 0x50000, v160
	global_load_dwordx4 v[170:173], v160, s[36:37] nt
	global_load_dwordx4 v[176:179], v160, s[36:37] offset:16 nt
	v_cvt_pk_bf16_f32 v92, v92, v93
	v_cvt_pk_bf16_f32 v93, v94, v95
	v_cvt_pk_bf16_f32 v94, v88, v89
	v_cvt_pk_bf16_f32 v95, v90, v91
	global_store_dwordx4 v161, v[92:95], s[8:9]
	s_waitcnt vmcnt(10)
	v_pk_fma_f32 v[86:87], v[86:87], v[134:135], v[182:183]
	v_pk_fma_f32 v[84:85], v[84:85], v[132:133], v[180:181]
	v_pk_fma_f32 v[82:83], v[82:83], v[130:131], v[186:187]
	v_pk_fma_f32 v[80:81], v[80:81], v[128:129], v[184:185]
	global_load_dwordx4 v[180:183], v160, s[36:37] offset:512 nt
	global_load_dwordx4 v[184:187], v160, s[36:37] offset:528 nt
	v_cvt_pk_bf16_f32 v84, v84, v85
	v_cvt_pk_bf16_f32 v85, v86, v87
	v_cvt_pk_bf16_f32 v86, v80, v81
	v_cvt_pk_bf16_f32 v87, v82, v83
	global_store_dwordx4 v161, v[84:87], s[8:9] offset:256
	v_add_u32_e32 v161, 0x8000, v161
	s_waitcnt vmcnt(10)
; __device__ __forceinline__ unsigned pk2(float lo, float hi) { f32x2 v = {lo, hi}; bf16x2_t b = __builtin_convertvector(v, bf16x2_t); return __builtin_bit_cast(unsigned, b); }
; __device__ __forceinline__ float bf_lo(unsigned u) { return __uint_as_float(u << 16); }
; __device__ __forceinline__ float bf_hi(unsigned u) { return __uint_as_float(u & 0xffff0000u); }
;     __device__ __forceinline__ void operator()(const AccT& acc, const Unit& u, int wr, int wc, int fr, int fq) const {
;         const int row0 = u.pm * BM + wr * 64 + fr; const int col0 = u.pn * BM + wc * 32 + 8 * fq; const int b = row0 >> 12;
;         f32x4 gt[2][2];
; #pragma unroll
;         for (int bj = 0; bj < 2; ++bj)
; #pragma unroll
;             for (int n = 0; n < 2; ++n) gt[bj][n] = *(const f32x4*)(gate + (size_t)b * NMOD + col0 + bj * HALF + n * 4);
; #pragma unroll
;         for (int ai = 0; ai < 2; ++ai)
; #pragma unroll
;             for (int m = 0; m < 4; ++m) { const size_t off = (size_t)(row0 + ai * HALF + m * 16) * DM + col0;
; #pragma unroll
;                 for (int bj = 0; bj < 2; ++bj) { f32x4 b0, b1;
;                     if constexpr (BB) { const u32x4 w = *(const u32x4*)((const bf16_t*)base + off + bj * HALF);
;                         b0 = (f32x4){bf_lo(w.x), bf_hi(w.x), bf_lo(w.y), bf_hi(w.y)}; b1 = (f32x4){bf_lo(w.z), bf_hi(w.z), bf_lo(w.w), bf_hi(w.w)}; }
;                     else { b0 = __builtin_nontemporal_load((const f32x4*)((const float*)base + off + bj * HALF)); b1 = __builtin_nontemporal_load((const f32x4*)((const float*)base + off + bj * HALF + 4)); }
;                     const f32x4 o0 = b0 + gt[bj][0] * acc[ai][bj][m][0], o1 = b1 + gt[bj][1] * acc[ai][bj][m][1];
;                     if constexpr (OB) { u32x4 w; w.x = pk2(o0[0], o0[1]); w.y = pk2(o0[2], o0[3]); w.z = pk2(o1[0], o1[1]); w.w = pk2(o1[2], o1[3]);
;                         *(u32x4*)((bf16_t*)out + off + bj * HALF) = w; }
;                     else { __builtin_nontemporal_store(o0, (f32x4*)((float*)out + off + bj * HALF)); __builtin_nontemporal_store(o1, (f32x4*)((float*)out + off + bj * HALF + 4)); } } }
;     }
	v_pk_fma_f32 v[78:79], v[78:79], v[142:143], v[190:191]
	v_pk_fma_f32 v[76:77], v[76:77], v[140:141], v[188:189]
	v_pk_fma_f32 v[74:75], v[74:75], v[138:139], v[194:195]
	v_pk_fma_f32 v[72:73], v[72:73], v[136:137], v[192:193]
	v_add_u32_e32 v160, 0x10000, v160
	global_load_dwordx4 v[188:191], v160, s[36:37] nt
	global_load_dwordx4 v[192:195], v160, s[36:37] offset:16 nt
	v_cvt_pk_bf16_f32 v76, v76, v77
	v_cvt_pk_bf16_f32 v77, v78, v79
	v_cvt_pk_bf16_f32 v78, v72, v73
	v_cvt_pk_bf16_f32 v79, v74, v75
	global_store_dwordx4 v161, v[76:79], s[8:9]
	s_waitcnt vmcnt(10)
	v_pk_fma_f32 v[70:71], v[70:71], v[134:135], v[198:199]
	v_pk_fma_f32 v[68:69], v[68:69], v[132:133], v[196:197]
	v_pk_fma_f32 v[66:67], v[66:67], v[130:131], v[202:203]
	v_pk_fma_f32 v[64:65], v[64:65], v[128:129], v[200:201]
	global_load_dwordx4 v[196:199], v160, s[36:37] offset:512 nt
	global_load_dwordx4 v[200:203], v160, s[36:37] offset:528 nt
	v_cvt_pk_bf16_f32 v68, v68, v69
	v_cvt_pk_bf16_f32 v69, v70, v71
	v_cvt_pk_bf16_f32 v70, v64, v65
	v_cvt_pk_bf16_f32 v71, v66, v67
	global_store_dwordx4 v161, v[68:71], s[8:9] offset:256
	v_add_u32_e32 v161, 0x28000, v161
	s_waitcnt vmcnt(10)
	v_pk_fma_f32 v[62:63], v[62:63], v[142:143], v[172:173]
	v_pk_fma_f32 v[60:61], v[60:61], v[140:141], v[170:171]
	v_pk_fma_f32 v[58:59], v[58:59], v[138:139], v[178:179]
	v_pk_fma_f32 v[56:57], v[56:57], v[136:137], v[176:177]
	v_add_u32_e32 v160, 0x10000, v160
	global_load_dwordx4 v[170:173], v160, s[36:37] nt
	global_load_dwordx4 v[176:179], v160, s[36:37] offset:16 nt
	v_cvt_pk_bf16_f32 v60, v60, v61
	v_cvt_pk_bf16_f32 v61, v62, v63
	v_cvt_pk_bf16_f32 v62, v56, v57
	v_cvt_pk_bf16_f32 v63, v58, v59
	global_store_dwordx4 v161, v[60:63], s[8:9]
	s_waitcnt vmcnt(10)
	v_pk_fma_f32 v[54:55], v[54:55], v[134:135], v[182:183]
	v_pk_fma_f32 v[52:53], v[52:53], v[132:133], v[180:181]
	v_pk_fma_f32 v[50:51], v[50:51], v[130:131], v[186:187]
	v_pk_fma_f32 v[48:49], v[48:49], v[128:129], v[184:185]
	global_load_dwordx4 v[180:183], v160, s[36:37] offset:512 nt
	global_load_dwordx4 v[184:187], v160, s[36:37] offset:528 nt
	v_cvt_pk_bf16_f32 v52, v52, v53
	v_cvt_pk_bf16_f32 v53, v54, v55
	v_cvt_pk_bf16_f32 v54, v48, v49
	v_cvt_pk_bf16_f32 v55, v50, v51
	global_store_dwordx4 v161, v[52:55], s[8:9] offset:256
	v_add_u32_e32 v161, 0x8000, v161
	s_waitcnt vmcnt(10)
	v_pk_fma_f32 v[46:47], v[46:47], v[142:143], v[190:191]
	v_pk_fma_f32 v[44:45], v[44:45], v[140:141], v[188:189]
	v_pk_fma_f32 v[42:43], v[42:43], v[138:139], v[194:195]
	v_pk_fma_f32 v[40:41], v[40:41], v[136:137], v[192:193]
	v_add_u32_e32 v160, 0x10000, v160
	global_load_dwordx4 v[188:191], v160, s[36:37] nt
	global_load_dwordx4 v[192:195], v160, s[36:37] offset:16 nt
	v_cvt_pk_bf16_f32 v44, v44, v45
	v_cvt_pk_bf16_f32 v45, v46, v47
	v_cvt_pk_bf16_f32 v46, v40, v41
	v_cvt_pk_bf16_f32 v47, v42, v43
	global_store_dwordx4 v161, v[44:47], s[8:9]
	s_waitcnt vmcnt(10)
	v_pk_fma_f32 v[38:39], v[38:39], v[134:135], v[198:199]
	v_pk_fma_f32 v[36:37], v[36:37], v[132:133], v[196:197]
	v_pk_fma_f32 v[34:35], v[34:35], v[130:131], v[202:203]
	v_pk_fma_f32 v[32:33], v[32:33], v[128:129], v[200:201]
	global_load_dwordx4 v[196:199], v160, s[36:37] offset:512 nt
	global_load_dwordx4 v[200:203], v160, s[36:37] offset:528 nt
	v_cvt_pk_bf16_f32 v36, v36, v37
	v_cvt_pk_bf16_f32 v37, v38, v39
	v_cvt_pk_bf16_f32 v38, v32, v33
	v_cvt_pk_bf16_f32 v39, v34, v35
	global_store_dwordx4 v161, v[36:39], s[8:9] offset:256
	v_add_u32_e32 v161, 0x8000, v161
	s_waitcnt vmcnt(10)
	v_pk_fma_f32 v[30:31], v[30:31], v[142:143], v[172:173]
	v_pk_fma_f32 v[28:29], v[28:29], v[140:141], v[170:171]
	v_pk_fma_f32 v[26:27], v[26:27], v[138:139], v[178:179]
	v_pk_fma_f32 v[24:25], v[24:25], v[136:137], v[176:177]
	v_cvt_pk_bf16_f32 v28, v28, v29
	v_cvt_pk_bf16_f32 v29, v30, v31
	v_cvt_pk_bf16_f32 v30, v24, v25
	v_cvt_pk_bf16_f32 v31, v26, v27
	global_store_dwordx4 v161, v[28:31], s[8:9]
	s_waitcnt vmcnt(8)
	v_pk_fma_f32 v[22:23], v[22:23], v[134:135], v[182:183]
	v_pk_fma_f32 v[20:21], v[20:21], v[132:133], v[180:181]
	v_pk_fma_f32 v[18:19], v[18:19], v[130:131], v[186:187]
	v_pk_fma_f32 v[16:17], v[16:17], v[128:129], v[184:185]
	v_cvt_pk_bf16_f32 v20, v20, v21
	v_cvt_pk_bf16_f32 v21, v22, v23
	v_cvt_pk_bf16_f32 v22, v16, v17
	v_cvt_pk_bf16_f32 v23, v18, v19
	global_store_dwordx4 v161, v[20:23], s[8:9] offset:256
	v_add_u32_e32 v161, 0x8000, v161
	s_waitcnt vmcnt(6)
	v_pk_fma_f32 v[14:15], v[14:15], v[142:143], v[190:191]
	v_pk_fma_f32 v[12:13], v[12:13], v[140:141], v[188:189]
	v_pk_fma_f32 v[10:11], v[10:11], v[138:139], v[194:195]
	v_pk_fma_f32 v[8:9], v[8:9], v[136:137], v[192:193]
	v_cvt_pk_bf16_f32 v12, v12, v13
	v_cvt_pk_bf16_f32 v13, v14, v15
	v_cvt_pk_bf16_f32 v14, v8, v9
	v_cvt_pk_bf16_f32 v15, v10, v11
	global_store_dwordx4 v161, v[12:15], s[8:9]
	s_waitcnt vmcnt(4)
	v_pk_fma_f32 v[6:7], v[6:7], v[134:135], v[198:199]
	v_pk_fma_f32 v[4:5], v[4:5], v[132:133], v[196:197]
	v_pk_fma_f32 v[2:3], v[2:3], v[130:131], v[202:203]
	v_pk_fma_f32 v[0:1], v[0:1], v[128:129], v[200:201]
	v_cvt_pk_bf16_f32 v4, v4, v5
	v_cvt_pk_bf16_f32 v5, v6, v7
	v_cvt_pk_bf16_f32 v6, v0, v1
	v_cvt_pk_bf16_f32 v7, v2, v3
	global_store_dwordx4 v161, v[4:7], s[8:9] offset:256
	s_andn2_b64 vcc, exec, s[0:1]
	s_mov_b64 s[0:1], -1
	s_cbranch_vccnz .LBB0_545
	s_andn2_b64 vcc, exec, s[6:7]
	s_cbranch_vccnz .LBB0_544
	s_barrier
	s_branch .LBB0_544
